# P1 gate-column tile: skip MFMA blocks on zero-padded / unused columns (bj=1 blocks; all blocks of waves with wc != 0)
# speedup vs baseline: 1.0094x; 1.0051x over previous
; #define LDA(dst, b, h) for (int m = 0; m < 4; ++m) for (int k = 0; k < 2; ++k) \
;     dst[m][k] = *reinterpret_cast<const bf16x8*>((char*)SA(b, h) + lds_byte(wr * 64 + m * 16 + fr, k * 32 + fq * 8))
; #define LDB(dst, b, h) for (int n = 0; n < 2; ++n) for (int k = 0; k < 2; ++k) \
;     dst[n][k] = *reinterpret_cast<const bf16x8*>((char*)SB(b, h) + lds_byte(wc * 32 + n * 16 + fr, k * 32 + fq * 8))
; #define MMA(ai, bj, At, Bq) do { __builtin_amdgcn_s_setprio(1); \
;     for (int m = 0; m < 4; ++m) for (int n = 0; n < 2; ++n) for (int k = 0; k < 2; ++k) \
;       acc[ai][bj][m][n] = __builtin_amdgcn_mfma_f32_16x16x32_bf16(At[m][k], Bq[n][k], acc[ai][bj][m][n], 0, 0, 0); \
;     __builtin_amdgcn_s_setprio(0); } while (0)
; #define WAIT_V(n) asm volatile("s_waitcnt vmcnt(" #n ")" ::: "memory")
; #define WAIT_L(n) asm volatile("s_waitcnt lgkmcnt(" #n ")" ::: "memory")
; #define BAR __builtin_amdgcn_s_barrier()
; #define SCHED __builtin_amdgcn_sched_barrier(0)
; template <class Epi>
; __device__ __forceinline__ void gemm_tile(const u16* __restrict__ A, const u16* __restrict__ Bt, int K,
;                                           int brow, int bcol, bool first, bool has_next, int nbrow, int nbcol, Epi epi) {
;     ...
;   f32x4 acc[2][2][4][2] = {};
;   bf16x8 At[4][2], B0[2][2], B1[2][2];
;   int nt = K / BK;
;   if (first) {
;     STAGE(SB(0, 0), Bt, bcol, 0); STAGE(SA(0, 0), A, brow, 0);
;     STAGE(SB(0, 1), Bt, bcol + HALF, 0); STAGE(SA(0, 1), A, brow + HALF, 0);
;     if (wr == 1) BAR;
;     WAIT_V(4); BAR;
;     STAGE(SB(1, 0), Bt, bcol, 1); STAGE(SA(1, 0), A, brow, 1); STAGE(SB(1, 1), Bt, bcol + HALF, 1);
;     WAIT_V(6); BAR;
;   } else {
;     if (wr == 1) BAR;
;     WAIT_V(16); BAR;
;   }
;   for (int t = 0; t < nt - 2; t += 2) {
;     LDB(B0, 0, 0); SCHED; LDA(At, 0, 0); STAGE(SA(1, 1), A, brow + HALF, t + 1);
;     WAIT_L(8); BAR; WAIT_L(0); MMA(0, 0, At, B0); BAR; SCHED;
.LBB0_142:
	v_and_b32_e32 v2, 15, v0
	v_lshlrev_b32_e32 v4, 2, v0
	v_and_b32_e32 v3, 48, v0
	v_lshlrev_b32_e32 v2, 6, v2
	v_and_b32_e32 v4, 32, v4
	v_lshlrev_b32_e32 v0, 6, v0
	s_movk_i32 s6, 0x3c0
	v_bitop3_b32 v2, v2, v4, v3 bitop3:0x36
	v_lshlrev_b32_e32 v9, 6, v152
	v_lshlrev_b32_e32 v1, 13, v1
	v_and_or_b32 v0, v0, s6, v3
	v_add_u32_e32 v5, s82, v2
	v_add_u32_e32 v6, s83, v2
	v_add_u32_e32 v7, s84, v2
	v_add_u32_e32 v8, s85, v2
	v_and_b32_e32 v9, 0x3000, v9
	v_add_u32_e32 v2, 16, v2
	v_xad_u32 v3, v0, v4, 16
	v_or_b32_e32 v4, 0x800, v1
	v_or_b32_e32 v10, 0x1000, v1
	v_or_b32_e32 v11, 0x1800, v1
	v_mov_b32_e32 v0, 0
	s_mov_b32 s44, -2
	v_add_u32_e32 v150, v5, v9
	v_add_u32_e32 v162, v2, v1
	v_add_u32_e32 v161, v3, v4
	v_add_u32_e32 v160, v3, v10
	v_add_u32_e32 v159, v3, v11
	v_add_u32_e32 v149, v6, v9
	v_add_u32_e32 v148, v7, v9
	v_add_u32_e32 v147, v8, v9
	s_mov_b64 s[6:7], s[34:35]
	v_mov_b32_e32 v1, v0
	v_mov_b64_e32 v[2:3], v[0:1]
	v_mov_b64_e32 v[4:5], v[0:1]
	v_mov_b64_e32 v[6:7], v[0:1]
	v_mov_b64_e32 v[8:9], v[0:1]
	v_mov_b64_e32 v[10:11], v[0:1]
	v_mov_b64_e32 v[12:13], v[0:1]
	v_mov_b64_e32 v[14:15], v[0:1]
	v_mov_b64_e32 v[16:17], v[0:1]
	v_mov_b64_e32 v[18:19], v[0:1]
	v_mov_b64_e32 v[20:21], v[0:1]
	v_mov_b64_e32 v[22:23], v[0:1]
	v_mov_b64_e32 v[24:25], v[0:1]
	v_mov_b64_e32 v[26:27], v[0:1]
	v_mov_b64_e32 v[28:29], v[0:1]
	v_mov_b64_e32 v[30:31], v[0:1]
	v_mov_b64_e32 v[32:33], v[0:1]
	v_mov_b64_e32 v[34:35], v[0:1]
	v_mov_b64_e32 v[36:37], v[0:1]
	v_mov_b64_e32 v[38:39], v[0:1]
	v_mov_b64_e32 v[40:41], v[0:1]
	v_mov_b64_e32 v[42:43], v[0:1]
	v_mov_b64_e32 v[44:45], v[0:1]
	v_mov_b64_e32 v[46:47], v[0:1]
	v_mov_b64_e32 v[48:49], v[0:1]
	v_mov_b64_e32 v[50:51], v[0:1]
	v_mov_b64_e32 v[52:53], v[0:1]
	v_mov_b64_e32 v[54:55], v[0:1]
	v_mov_b64_e32 v[56:57], v[0:1]
	v_mov_b64_e32 v[58:59], v[0:1]
	v_mov_b64_e32 v[60:61], v[0:1]
	v_mov_b64_e32 v[62:63], v[0:1]
	v_mov_b64_e32 v[64:65], v[0:1]
	v_mov_b64_e32 v[66:67], v[0:1]
	v_mov_b64_e32 v[68:69], v[0:1]
	v_mov_b64_e32 v[70:71], v[0:1]
	v_mov_b64_e32 v[72:73], v[0:1]
	v_mov_b64_e32 v[74:75], v[0:1]
	v_mov_b64_e32 v[76:77], v[0:1]
	v_mov_b64_e32 v[78:79], v[0:1]
	v_mov_b64_e32 v[80:81], v[0:1]
	v_mov_b64_e32 v[82:83], v[0:1]
	v_mov_b64_e32 v[84:85], v[0:1]
	v_mov_b64_e32 v[86:87], v[0:1]
	v_mov_b64_e32 v[88:89], v[0:1]
	v_mov_b64_e32 v[90:91], v[0:1]
	v_mov_b64_e32 v[92:93], v[0:1]
	v_mov_b64_e32 v[94:95], v[0:1]
	v_mov_b64_e32 v[96:97], v[0:1]
	v_mov_b64_e32 v[98:99], v[0:1]
	v_mov_b64_e32 v[100:101], v[0:1]
	v_mov_b64_e32 v[102:103], v[0:1]
	v_mov_b64_e32 v[104:105], v[0:1]
	v_mov_b64_e32 v[106:107], v[0:1]
	v_mov_b64_e32 v[108:109], v[0:1]
	v_mov_b64_e32 v[110:111], v[0:1]
	v_mov_b64_e32 v[112:113], v[0:1]
	v_mov_b64_e32 v[114:115], v[0:1]
	v_mov_b64_e32 v[116:117], v[0:1]
	v_mov_b64_e32 v[118:119], v[0:1]
	v_mov_b64_e32 v[120:121], v[0:1]
	v_mov_b64_e32 v[122:123], v[0:1]
	v_mov_b64_e32 v[124:125], v[0:1]
	v_mov_b64_e32 v[126:127], v[0:1]
	v_lshl_add_u64 v[128:129], v[164:165], 0, s[8:9]
	v_lshl_add_u64 v[130:131], v[132:133], 0, s[8:9]
	v_lshl_add_u64 v[134:135], v[164:165], 0, s[10:11]
	v_lshl_add_u64 v[136:137], v[132:133], 0, s[10:11]
	v_lshl_add_u64 v[138:139], v[164:165], 0, s[64:65]
	v_lshl_add_u64 v[140:141], v[132:133], 0, s[64:65]
	v_lshl_add_u64 v[142:143], v[164:165], 0, s[4:5]
	v_lshl_add_u64 v[144:145], v[132:133], 0, s[4:5]
	s_lshr_b32 s99, s58, 8
	s_cmp_eq_u32 s99, 12
	s_cselect_b32 s99, 1, 0
	s_bfe_u32 s98, s33, 0x20006
	s_cmp_lg_u32 s98, 0
	s_cselect_b32 s98, 1, 0
	s_and_b32 s98, s98, s99
.LBB0_143:
	ds_read_b128 v[166:169], v150
	ds_read_b128 v[174:177], v150 offset:1024
	ds_read_b128 v[178:181], v150 offset:2048
	ds_read_b128 v[182:185], v150 offset:3072
	v_add_u32_e32 v151, 0xc000, v157
	v_lshl_add_u64 v[170:171], s[6:7], 0, v[142:143]
	v_readfirstlane_b32 s8, v151
	v_lshl_add_u64 v[172:173], v[170:171], 0, s[20:21]
	s_mov_b32 m0, s8
	ds_read_b128 v[186:189], v162
	ds_read_b128 v[190:193], v162 offset:1024
	ds_read_b128 v[194:197], v161
	ds_read_b128 v[198:201], v161 offset:1024
	ds_read_b128 v[202:205], v160
	ds_read_b128 v[206:209], v160 offset:1024
	ds_read_b128 v[210:213], v159
	ds_read_b128 v[214:217], v159 offset:1024
	global_load_lds_dwordx4 v[172:173], off
	v_add_u32_e32 v173, 0xe000, v157
	v_lshl_add_u64 v[222:223], s[6:7], 0, v[144:145]
	v_readfirstlane_b32 s8, v173
	v_lshl_add_u64 v[218:219], v[222:223], 0, s[20:21]
	s_mov_b32 m0, s8
	s_nop 0
	global_load_lds_dwordx4 v[218:219], off
	s_waitcnt lgkmcnt(8)
	s_barrier
	s_waitcnt lgkmcnt(0)
	s_cmp_lg_u32 s98, 0
	s_cbranch_scc1 .Lmy_glr_skip_0
	s_setprio 1
	s_waitcnt lgkmcnt(0)
	v_mfma_f32_16x16x32_bf16 v[124:127], v[186:189], v[166:169], v[124:127]
	v_mfma_f32_16x16x32_bf16 v[120:123], v[186:189], v[178:181], v[120:123]
	v_mfma_f32_16x16x32_bf16 v[116:119], v[194:197], v[166:169], v[116:119]
	v_mfma_f32_16x16x32_bf16 v[112:115], v[194:197], v[178:181], v[112:115]
	v_mfma_f32_16x16x32_bf16 v[108:111], v[202:205], v[166:169], v[108:111]
	v_mfma_f32_16x16x32_bf16 v[104:107], v[202:205], v[178:181], v[104:107]
	v_mfma_f32_16x16x32_bf16 v[100:103], v[210:213], v[166:169], v[100:103]
	v_mfma_f32_16x16x32_bf16 v[96:99], v[210:213], v[178:181], v[96:99]
	v_mfma_f32_16x16x32_bf16 v[124:127], v[190:193], v[174:177], v[124:127]
	v_mfma_f32_16x16x32_bf16 v[120:123], v[190:193], v[182:185], v[120:123]
	v_mfma_f32_16x16x32_bf16 v[116:119], v[198:201], v[174:177], v[116:119]
	v_mfma_f32_16x16x32_bf16 v[112:115], v[198:201], v[182:185], v[112:115]
	v_mfma_f32_16x16x32_bf16 v[108:111], v[206:209], v[174:177], v[108:111]
	v_mfma_f32_16x16x32_bf16 v[104:107], v[206:209], v[182:185], v[104:107]
	v_mfma_f32_16x16x32_bf16 v[100:103], v[214:217], v[174:177], v[100:103]
	v_mfma_f32_16x16x32_bf16 v[96:99], v[214:217], v[182:185], v[96:99]
	s_setprio 0
; #define LDA(dst, b, h) for (int m = 0; m < 4; ++m) for (int k = 0; k < 2; ++k) \
;     dst[m][k] = *reinterpret_cast<const bf16x8*>((char*)SA(b, h) + lds_byte(wr * 64 + m * 16 + fr, k * 32 + fq * 8))
; #define LDB(dst, b, h) for (int n = 0; n < 2; ++n) for (int k = 0; k < 2; ++k) \
;     dst[n][k] = *reinterpret_cast<const bf16x8*>((char*)SB(b, h) + lds_byte(wc * 32 + n * 16 + fr, k * 32 + fq * 8))
; #define MMA(ai, bj, At, Bq) do { __builtin_amdgcn_s_setprio(1); \
;     for (int m = 0; m < 4; ++m) for (int n = 0; n < 2; ++n) for (int k = 0; k < 2; ++k) \
;       acc[ai][bj][m][n] = __builtin_amdgcn_mfma_f32_16x16x32_bf16(At[m][k], Bq[n][k], acc[ai][bj][m][n], 0, 0, 0); \
;     __builtin_amdgcn_s_setprio(0); } while (0)
; #define WAIT_V(n) asm volatile("s_waitcnt vmcnt(" #n ")" ::: "memory")
; #define WAIT_L(n) asm volatile("s_waitcnt lgkmcnt(" #n ")" ::: "memory")
; #define BAR __builtin_amdgcn_s_barrier()
; #define SCHED __builtin_amdgcn_sched_barrier(0)
; template <class Epi>
; __device__ __forceinline__ void gemm_tile(const u16* __restrict__ A, const u16* __restrict__ Bt, int K,
;                                           int brow, int bcol, bool first, bool has_next, int nbrow, int nbcol, Epi epi) {
;     ...
;     WAIT_L(8); BAR; WAIT_L(0); MMA(0, 0, At, B0); BAR; SCHED;
;     LDB(B1, 0, 1); STAGE(SB(0, 0), Bt, bcol, t + 2);
;     BAR; WAIT_L(0); MMA(0, 1, At, B1); BAR;
;     LDA(At, 0, 1); STAGE(SA(0, 0), A, brow, t + 2);
;     BAR; WAIT_L(0); MMA(1, 0, At, B0); BAR; SCHED;
;     STAGE(SB(0, 1), Bt, bcol + HALF, t + 2);
;     WAIT_V(6); BAR; MMA(1, 1, At, B1); BAR;
.Lmy_glr_skip_0:
	s_barrier
	v_lshl_add_u64 v[246:247], s[6:7], 0, v[128:129]
	v_readfirstlane_b32 s8, v158
	v_add_u32_e32 v163, 0x2000, v158
	v_lshl_add_u64 v[242:243], v[246:247], 0, s[22:23]
	s_mov_b32 m0, s8
	v_lshl_add_u64 v[248:249], s[6:7], 0, v[130:131]
	v_readfirstlane_b32 s8, v163
	ds_read_b128 v[218:221], v149
	ds_read_b128 v[230:233], v149 offset:1024
	ds_read_b128 v[234:237], v149 offset:2048
	ds_read_b128 v[238:241], v149 offset:3072
	global_load_lds_dwordx4 v[242:243], off
	v_lshl_add_u64 v[242:243], v[248:249], 0, s[22:23]
	s_mov_b32 m0, s8
	s_nop 0
	global_load_lds_dwordx4 v[242:243], off
	s_barrier
	s_waitcnt lgkmcnt(0)
	s_cmp_lg_u32 s99, 0
	s_cbranch_scc1 .Lmy_glr_skip_1
	s_setprio 1
	s_waitcnt lgkmcnt(0)
	v_mfma_f32_16x16x32_bf16 v[92:95], v[186:189], v[218:221], v[92:95]
	v_mfma_f32_16x16x32_bf16 v[88:91], v[186:189], v[234:237], v[88:91]
	v_mfma_f32_16x16x32_bf16 v[84:87], v[194:197], v[218:221], v[84:87]
	v_mfma_f32_16x16x32_bf16 v[80:83], v[194:197], v[234:237], v[80:83]
	v_mfma_f32_16x16x32_bf16 v[76:79], v[202:205], v[218:221], v[76:79]
	v_mfma_f32_16x16x32_bf16 v[72:75], v[202:205], v[234:237], v[72:75]
	v_mfma_f32_16x16x32_bf16 v[68:71], v[210:213], v[218:221], v[68:71]
	v_mfma_f32_16x16x32_bf16 v[64:67], v[210:213], v[234:237], v[64:67]
	v_mfma_f32_16x16x32_bf16 v[92:95], v[190:193], v[230:233], v[92:95]
	v_mfma_f32_16x16x32_bf16 v[88:91], v[190:193], v[238:241], v[88:91]
	v_mfma_f32_16x16x32_bf16 v[84:87], v[198:201], v[230:233], v[84:87]
	v_mfma_f32_16x16x32_bf16 v[80:83], v[198:201], v[238:241], v[80:83]
	v_mfma_f32_16x16x32_bf16 v[76:79], v[206:209], v[230:233], v[76:79]
	v_mfma_f32_16x16x32_bf16 v[72:75], v[206:209], v[238:241], v[72:75]
	v_mfma_f32_16x16x32_bf16 v[68:71], v[214:217], v[230:233], v[68:71]
	v_mfma_f32_16x16x32_bf16 v[64:67], v[214:217], v[238:241], v[64:67]
	s_setprio 0
.Lmy_glr_skip_1:
	v_lshl_add_u64 v[250:251], s[6:7], 0, v[134:135]
	v_readfirstlane_b32 s8, v157
	v_lshl_add_u64 v[242:243], v[250:251], 0, s[24:25]
	s_mov_b32 m0, s8
	v_lshl_add_u64 v[252:253], s[6:7], 0, v[136:137]
	v_readfirstlane_b32 s8, v156
	s_barrier
	ds_read_b128 v[186:189], v162 offset:16384
	ds_read_b128 v[190:193], v162 offset:17408
	ds_read_b128 v[194:197], v161 offset:16384
	ds_read_b128 v[198:201], v161 offset:17408
	ds_read_b128 v[202:205], v160 offset:16384
	ds_read_b128 v[206:209], v160 offset:17408
	ds_read_b128 v[210:213], v159 offset:16384
	ds_read_b128 v[214:217], v159 offset:17408
	global_load_lds_dwordx4 v[242:243], off
	v_lshl_add_u64 v[242:243], v[252:253], 0, s[24:25]
	s_mov_b32 m0, s8
	s_nop 0
	global_load_lds_dwordx4 v[242:243], off
	s_barrier
	s_waitcnt lgkmcnt(0)
	s_cmp_lg_u32 s98, 0
	s_cbranch_scc1 .Lmy_glr_skip_2
	s_setprio 1
	s_waitcnt lgkmcnt(0)
	v_mfma_f32_16x16x32_bf16 v[60:63], v[186:189], v[166:169], v[60:63]
	v_mfma_f32_16x16x32_bf16 v[56:59], v[186:189], v[178:181], v[56:59]
	v_mfma_f32_16x16x32_bf16 v[52:55], v[194:197], v[166:169], v[52:55]
	v_mfma_f32_16x16x32_bf16 v[48:51], v[194:197], v[178:181], v[48:51]
	v_mfma_f32_16x16x32_bf16 v[44:47], v[202:205], v[166:169], v[44:47]
	v_mfma_f32_16x16x32_bf16 v[40:43], v[202:205], v[178:181], v[40:43]
	v_mfma_f32_16x16x32_bf16 v[36:39], v[210:213], v[166:169], v[36:39]
	v_mfma_f32_16x16x32_bf16 v[32:35], v[210:213], v[178:181], v[32:35]
	v_mfma_f32_16x16x32_bf16 v[60:63], v[190:193], v[174:177], v[60:63]
	v_mfma_f32_16x16x32_bf16 v[56:59], v[190:193], v[182:185], v[56:59]
	v_mfma_f32_16x16x32_bf16 v[52:55], v[198:201], v[174:177], v[52:55]
	v_mfma_f32_16x16x32_bf16 v[48:51], v[198:201], v[182:185], v[48:51]
	v_mfma_f32_16x16x32_bf16 v[44:47], v[206:209], v[174:177], v[44:47]
	v_mfma_f32_16x16x32_bf16 v[40:43], v[206:209], v[182:185], v[40:43]
	v_mfma_f32_16x16x32_bf16 v[36:39], v[214:217], v[174:177], v[36:39]
	v_mfma_f32_16x16x32_bf16 v[32:35], v[214:217], v[182:185], v[32:35]
	s_setprio 0
.Lmy_glr_skip_2:
	s_barrier
	v_lshl_add_u64 v[228:229], s[6:7], 0, v[138:139]
	v_readfirstlane_b32 s8, v155
	v_lshl_add_u64 v[166:167], v[228:229], 0, s[22:23]
	s_mov_b32 m0, s8
	v_lshl_add_u64 v[224:225], s[6:7], 0, v[140:141]
	global_load_lds_dwordx4 v[166:167], off
	v_add_u32_e32 v166, 0x2000, v155
	v_lshl_add_u64 v[168:169], v[224:225], 0, s[22:23]
	v_readfirstlane_b32 s8, v166
	s_mov_b32 m0, s8
	s_nop 0
	global_load_lds_dwordx4 v[168:169], off
	s_waitcnt vmcnt(6)
	s_barrier
	s_cmp_lg_u32 s99, 0
	s_cbranch_scc1 .Lmy_glr_skip_3
	s_setprio 1
	v_mfma_f32_16x16x32_bf16 v[28:31], v[186:189], v[218:221], v[28:31]
	v_mfma_f32_16x16x32_bf16 v[24:27], v[186:189], v[234:237], v[24:27]
	v_mfma_f32_16x16x32_bf16 v[20:23], v[194:197], v[218:221], v[20:23]
	v_mfma_f32_16x16x32_bf16 v[16:19], v[194:197], v[234:237], v[16:19]
	v_mfma_f32_16x16x32_bf16 v[12:15], v[202:205], v[218:221], v[12:15]
	v_mfma_f32_16x16x32_bf16 v[8:11], v[202:205], v[234:237], v[8:11]
	v_mfma_f32_16x16x32_bf16 v[4:7], v[210:213], v[218:221], v[4:7]
	v_mfma_f32_16x16x32_bf16 v[0:3], v[210:213], v[234:237], v[0:3]
	v_mfma_f32_16x16x32_bf16 v[28:31], v[190:193], v[230:233], v[28:31]
	v_mfma_f32_16x16x32_bf16 v[24:27], v[190:193], v[238:241], v[24:27]
	v_mfma_f32_16x16x32_bf16 v[20:23], v[198:201], v[230:233], v[20:23]
	v_mfma_f32_16x16x32_bf16 v[16:19], v[198:201], v[238:241], v[16:19]
	v_mfma_f32_16x16x32_bf16 v[12:15], v[206:209], v[230:233], v[12:15]
	v_mfma_f32_16x16x32_bf16 v[8:11], v[206:209], v[238:241], v[8:11]
	v_mfma_f32_16x16x32_bf16 v[4:7], v[214:217], v[230:233], v[4:7]
	v_mfma_f32_16x16x32_bf16 v[0:3], v[214:217], v[238:241], v[0:3]
	s_setprio 0
; #define LDA(dst, b, h) for (int m = 0; m < 4; ++m) for (int k = 0; k < 2; ++k) \
;     dst[m][k] = *reinterpret_cast<const bf16x8*>((char*)SA(b, h) + lds_byte(wr * 64 + m * 16 + fr, k * 32 + fq * 8))
; #define LDB(dst, b, h) for (int n = 0; n < 2; ++n) for (int k = 0; k < 2; ++k) \
;     dst[n][k] = *reinterpret_cast<const bf16x8*>((char*)SB(b, h) + lds_byte(wc * 32 + n * 16 + fr, k * 32 + fq * 8))
; #define MMA(ai, bj, At, Bq) do { __builtin_amdgcn_s_setprio(1); \
;     for (int m = 0; m < 4; ++m) for (int n = 0; n < 2; ++n) for (int k = 0; k < 2; ++k) \
;       acc[ai][bj][m][n] = __builtin_amdgcn_mfma_f32_16x16x32_bf16(At[m][k], Bq[n][k], acc[ai][bj][m][n], 0, 0, 0); \
;     __builtin_amdgcn_s_setprio(0); } while (0)
; #define WAIT_L(n) asm volatile("s_waitcnt lgkmcnt(" #n ")" ::: "memory")
; #define BAR __builtin_amdgcn_s_barrier()
; #define SCHED __builtin_amdgcn_sched_barrier(0)
; template <class Epi>
; __device__ __forceinline__ void gemm_tile(const u16* __restrict__ A, const u16* __restrict__ Bt, int K,
;                                           int brow, int bcol, bool first, bool has_next, int nbrow, int nbcol, Epi epi) {
;     ...
;     LDB(B0, 1, 0); SCHED; LDA(At, 1, 0); STAGE(SA(0, 1), A, brow + HALF, t + 2);
;     WAIT_L(8); BAR; WAIT_L(0); MMA(0, 0, At, B0); BAR; SCHED;
;     LDB(B1, 1, 1); STAGE(SB(1, 0), Bt, bcol, t + 3);
;     BAR; WAIT_L(0); MMA(0, 1, At, B1); BAR;
;     LDA(At, 1, 1); STAGE(SA(1, 0), A, brow, t + 3);
;     BAR; WAIT_L(0); MMA(1, 0, At, B0); BAR; SCHED;
.Lmy_glr_skip_3:
	s_barrier
	ds_read_b128 v[174:177], v148
	ds_read_b128 v[178:181], v148 offset:1024
	ds_read_b128 v[182:185], v148 offset:2048
	ds_read_b128 v[186:189], v148 offset:3072
	v_readfirstlane_b32 s8, v154
	v_lshl_add_u64 v[168:169], v[170:171], 0, s[24:25]
	s_mov_b32 m0, s8
	v_readfirstlane_b32 s8, v153
	ds_read_b128 v[190:193], v162 offset:32768
	ds_read_b128 v[194:197], v162 offset:33792
	ds_read_b128 v[198:201], v161 offset:32768
	ds_read_b128 v[202:205], v161 offset:33792
	ds_read_b128 v[206:209], v160 offset:32768
	ds_read_b128 v[210:213], v160 offset:33792
	ds_read_b128 v[214:217], v159 offset:32768
	ds_read_b128 v[218:221], v159 offset:33792
	global_load_lds_dwordx4 v[168:169], off
	v_lshl_add_u64 v[168:169], v[222:223], 0, s[24:25]
	s_mov_b32 m0, s8
	s_nop 0
	global_load_lds_dwordx4 v[168:169], off
	s_waitcnt lgkmcnt(8)
	s_barrier
	s_waitcnt lgkmcnt(0)
	s_cmp_lg_u32 s98, 0
	s_cbranch_scc1 .Lmy_glr_skip_4
	s_setprio 1
	s_waitcnt lgkmcnt(0)
	v_mfma_f32_16x16x32_bf16 v[124:127], v[190:193], v[174:177], v[124:127]
	v_mfma_f32_16x16x32_bf16 v[120:123], v[190:193], v[182:185], v[120:123]
	v_mfma_f32_16x16x32_bf16 v[116:119], v[198:201], v[174:177], v[116:119]
	v_mfma_f32_16x16x32_bf16 v[112:115], v[198:201], v[182:185], v[112:115]
	v_mfma_f32_16x16x32_bf16 v[108:111], v[206:209], v[174:177], v[108:111]
	v_mfma_f32_16x16x32_bf16 v[104:107], v[206:209], v[182:185], v[104:107]
	v_mfma_f32_16x16x32_bf16 v[100:103], v[214:217], v[174:177], v[100:103]
	v_mfma_f32_16x16x32_bf16 v[96:99], v[214:217], v[182:185], v[96:99]
	v_mfma_f32_16x16x32_bf16 v[124:127], v[194:197], v[178:181], v[124:127]
	v_mfma_f32_16x16x32_bf16 v[120:123], v[194:197], v[186:189], v[120:123]
	v_mfma_f32_16x16x32_bf16 v[116:119], v[202:205], v[178:181], v[116:119]
	v_mfma_f32_16x16x32_bf16 v[112:115], v[202:205], v[186:189], v[112:115]
	v_mfma_f32_16x16x32_bf16 v[108:111], v[210:213], v[178:181], v[108:111]
	v_mfma_f32_16x16x32_bf16 v[104:107], v[210:213], v[186:189], v[104:107]
	v_mfma_f32_16x16x32_bf16 v[100:103], v[218:221], v[178:181], v[100:103]
	v_mfma_f32_16x16x32_bf16 v[96:99], v[218:221], v[186:189], v[96:99]
	s_setprio 0
.Lmy_glr_skip_4:
	s_barrier
	v_add_u32_e32 v167, s84, v146
	v_lshl_add_u64 v[168:169], v[246:247], 0, s[26:27]
	v_readfirstlane_b32 s8, v167
	s_mov_b32 m0, s8
	ds_read_b128 v[230:233], v147
	ds_read_b128 v[234:237], v147 offset:1024
	ds_read_b128 v[238:241], v147 offset:2048
	ds_read_b128 v[242:245], v147 offset:3072
	global_load_lds_dwordx4 v[168:169], off
	v_add_u32_e32 v168, 0x2000, v167
	v_lshl_add_u64 v[170:171], v[248:249], 0, s[26:27]
	v_readfirstlane_b32 s8, v168
	s_mov_b32 m0, s8
	s_nop 0
	global_load_lds_dwordx4 v[170:171], off
	s_barrier
	s_waitcnt lgkmcnt(0)
	s_cmp_lg_u32 s99, 0
	s_cbranch_scc1 .Lmy_glr_skip_5
	s_setprio 1
	s_waitcnt lgkmcnt(0)
	v_mfma_f32_16x16x32_bf16 v[92:95], v[190:193], v[230:233], v[92:95]
	v_mfma_f32_16x16x32_bf16 v[88:91], v[190:193], v[238:241], v[88:91]
	v_mfma_f32_16x16x32_bf16 v[84:87], v[198:201], v[230:233], v[84:87]
	v_mfma_f32_16x16x32_bf16 v[80:83], v[198:201], v[238:241], v[80:83]
	v_mfma_f32_16x16x32_bf16 v[76:79], v[206:209], v[230:233], v[76:79]
	v_mfma_f32_16x16x32_bf16 v[72:75], v[206:209], v[238:241], v[72:75]
	v_mfma_f32_16x16x32_bf16 v[68:71], v[214:217], v[230:233], v[68:71]
	v_mfma_f32_16x16x32_bf16 v[64:67], v[214:217], v[238:241], v[64:67]
	v_mfma_f32_16x16x32_bf16 v[92:95], v[194:197], v[234:237], v[92:95]
	v_mfma_f32_16x16x32_bf16 v[88:91], v[194:197], v[242:245], v[88:91]
	v_mfma_f32_16x16x32_bf16 v[84:87], v[202:205], v[234:237], v[84:87]
	v_mfma_f32_16x16x32_bf16 v[80:83], v[202:205], v[242:245], v[80:83]
	v_mfma_f32_16x16x32_bf16 v[76:79], v[210:213], v[234:237], v[76:79]
	v_mfma_f32_16x16x32_bf16 v[72:75], v[210:213], v[242:245], v[72:75]
	v_mfma_f32_16x16x32_bf16 v[68:71], v[218:221], v[234:237], v[68:71]
	v_mfma_f32_16x16x32_bf16 v[64:67], v[218:221], v[242:245], v[64:67]
	s_setprio 0
.Lmy_glr_skip_5:
	v_add_u32_e32 v169, 0x8000, v157
	v_lshl_add_u64 v[170:171], v[250:251], 0, s[28:29]
	v_readfirstlane_b32 s8, v169
	s_mov_b32 m0, s8
	s_barrier
	ds_read_b128 v[190:193], v162 offset:49152
	ds_read_b128 v[194:197], v162 offset:50176
	ds_read_b128 v[198:201], v161 offset:49152
	ds_read_b128 v[202:205], v161 offset:50176
	ds_read_b128 v[206:209], v160 offset:49152
	ds_read_b128 v[210:213], v160 offset:50176
	ds_read_b128 v[214:217], v159 offset:49152
	ds_read_b128 v[218:221], v159 offset:50176
	global_load_lds_dwordx4 v[170:171], off
	v_add_u32_e32 v170, 0xa000, v157
	v_lshl_add_u64 v[222:223], v[252:253], 0, s[28:29]
	v_readfirstlane_b32 s8, v170
	s_mov_b32 m0, s8
	s_nop 0
	global_load_lds_dwordx4 v[222:223], off
	s_barrier
	s_waitcnt lgkmcnt(0)
	s_cmp_lg_u32 s98, 0
	s_cbranch_scc1 .Lmy_glr_skip_6
	s_setprio 1
	s_waitcnt lgkmcnt(0)
	v_mfma_f32_16x16x32_bf16 v[60:63], v[190:193], v[174:177], v[60:63]
	v_mfma_f32_16x16x32_bf16 v[56:59], v[190:193], v[182:185], v[56:59]
	v_mfma_f32_16x16x32_bf16 v[52:55], v[198:201], v[174:177], v[52:55]
	v_mfma_f32_16x16x32_bf16 v[48:51], v[198:201], v[182:185], v[48:51]
	v_mfma_f32_16x16x32_bf16 v[44:47], v[206:209], v[174:177], v[44:47]
	v_mfma_f32_16x16x32_bf16 v[40:43], v[206:209], v[182:185], v[40:43]
	v_mfma_f32_16x16x32_bf16 v[36:39], v[214:217], v[174:177], v[36:39]
	v_mfma_f32_16x16x32_bf16 v[32:35], v[214:217], v[182:185], v[32:35]
	v_mfma_f32_16x16x32_bf16 v[60:63], v[194:197], v[178:181], v[60:63]
	v_mfma_f32_16x16x32_bf16 v[56:59], v[194:197], v[186:189], v[56:59]
	v_mfma_f32_16x16x32_bf16 v[52:55], v[202:205], v[178:181], v[52:55]
	v_mfma_f32_16x16x32_bf16 v[48:51], v[202:205], v[186:189], v[48:51]
	v_mfma_f32_16x16x32_bf16 v[44:47], v[210:213], v[178:181], v[44:47]
	v_mfma_f32_16x16x32_bf16 v[40:43], v[210:213], v[186:189], v[40:43]
	v_mfma_f32_16x16x32_bf16 v[36:39], v[218:221], v[178:181], v[36:39]
	v_mfma_f32_16x16x32_bf16 v[32:35], v[218:221], v[186:189], v[32:35]
	s_setprio 0
; #define LDA(dst, b, h) for (int m = 0; m < 4; ++m) for (int k = 0; k < 2; ++k) \
;     dst[m][k] = *reinterpret_cast<const bf16x8*>((char*)SA(b, h) + lds_byte(wr * 64 + m * 16 + fr, k * 32 + fq * 8))
; #define LDB(dst, b, h) for (int n = 0; n < 2; ++n) for (int k = 0; k < 2; ++k) \
;     dst[n][k] = *reinterpret_cast<const bf16x8*>((char*)SB(b, h) + lds_byte(wc * 32 + n * 16 + fr, k * 32 + fq * 8))
; #define MMA(ai, bj, At, Bq) do { __builtin_amdgcn_s_setprio(1); \
;     for (int m = 0; m < 4; ++m) for (int n = 0; n < 2; ++n) for (int k = 0; k < 2; ++k) \
;       acc[ai][bj][m][n] = __builtin_amdgcn_mfma_f32_16x16x32_bf16(At[m][k], Bq[n][k], acc[ai][bj][m][n], 0, 0, 0); \
;     __builtin_amdgcn_s_setprio(0); } while (0)
; #define WAIT_V(n) asm volatile("s_waitcnt vmcnt(" #n ")" ::: "memory")
; #define WAIT_L(n) asm volatile("s_waitcnt lgkmcnt(" #n ")" ::: "memory")
; #define BAR __builtin_amdgcn_s_barrier()
; template <class Epi>
; __device__ __forceinline__ void gemm_tile(const u16* __restrict__ A, const u16* __restrict__ Bt, int K,
;                                           int brow, int bcol, bool first, bool has_next, int nbrow, int nbcol, Epi epi) {
;     ...
;     STAGE(SB(1, 1), Bt, bcol + HALF, t + 3);
;     WAIT_V(6); BAR; MMA(1, 1, At, B1); BAR;
;   }
;   { LDB(B0, 0, 0); LDA(At, 0, 0); STAGE(SA(1, 1), A, brow + HALF, nt - 1);
;     BAR; WAIT_L(0); MMA(0, 0, At, B0); BAR;
;     LDB(B1, 0, 1); BAR; WAIT_L(0); MMA(0, 1, At, B1); BAR;
.Lmy_glr_skip_6:
	s_barrier
	v_add_u32_e32 v171, s85, v146
	v_add_u32_e32 v172, 0x2000, v171
	v_readfirstlane_b32 s8, v171
	v_lshl_add_u64 v[174:175], v[228:229], 0, s[26:27]
	s_mov_b32 m0, s8
	v_readfirstlane_b32 s8, v172
	global_load_lds_dwordx4 v[174:175], off
	v_lshl_add_u64 v[174:175], v[224:225], 0, s[26:27]
	s_mov_b32 m0, s8
	s_nop 0
	global_load_lds_dwordx4 v[174:175], off
	s_waitcnt vmcnt(6)
	s_barrier
	s_cmp_lg_u32 s99, 0
	s_cbranch_scc1 .Lmy_glr_skip_7
	s_setprio 1
	v_mfma_f32_16x16x32_bf16 v[28:31], v[190:193], v[230:233], v[28:31]
	v_mfma_f32_16x16x32_bf16 v[24:27], v[190:193], v[238:241], v[24:27]
	v_mfma_f32_16x16x32_bf16 v[20:23], v[198:201], v[230:233], v[20:23]
	v_mfma_f32_16x16x32_bf16 v[16:19], v[198:201], v[238:241], v[16:19]
	v_mfma_f32_16x16x32_bf16 v[12:15], v[206:209], v[230:233], v[12:15]
	v_mfma_f32_16x16x32_bf16 v[8:11], v[206:209], v[238:241], v[8:11]
	v_mfma_f32_16x16x32_bf16 v[4:7], v[214:217], v[230:233], v[4:7]
	v_mfma_f32_16x16x32_bf16 v[0:3], v[214:217], v[238:241], v[0:3]
	v_mfma_f32_16x16x32_bf16 v[28:31], v[194:197], v[234:237], v[28:31]
	v_mfma_f32_16x16x32_bf16 v[24:27], v[194:197], v[242:245], v[24:27]
	v_mfma_f32_16x16x32_bf16 v[20:23], v[202:205], v[234:237], v[20:23]
	v_mfma_f32_16x16x32_bf16 v[16:19], v[202:205], v[242:245], v[16:19]
	v_mfma_f32_16x16x32_bf16 v[12:15], v[210:213], v[234:237], v[12:15]
	v_mfma_f32_16x16x32_bf16 v[8:11], v[210:213], v[242:245], v[8:11]
	v_mfma_f32_16x16x32_bf16 v[4:7], v[218:221], v[234:237], v[4:7]
	v_mfma_f32_16x16x32_bf16 v[0:3], v[218:221], v[242:245], v[0:3]
	s_setprio 0
.Lmy_glr_skip_7:
	s_add_i32 s44, s44, 2
	s_add_u32 s6, s6, 0x100
	s_addc_u32 s7, s7, 0
	s_cmp_lt_u32 s44, 12
	s_barrier
	s_cbranch_scc1 .LBB0_143
	s_add_u32 s4, s34, s4
	s_addc_u32 s5, s35, s5
	v_lshl_add_u64 v[206:207], s[4:5], 0, v[164:165]
	v_readfirstlane_b32 s6, v151
	ds_read_b128 v[128:131], v150
	ds_read_b128 v[134:137], v150 offset:1024
	ds_read_b128 v[138:141], v150 offset:2048
	ds_read_b128 v[142:145], v150 offset:3072
	ds_read_b128 v[174:177], v162
	ds_read_b128 v[178:181], v162 offset:1024
	ds_read_b128 v[182:185], v161
	ds_read_b128 v[186:189], v161 offset:1024
	ds_read_b128 v[190:193], v160
	ds_read_b128 v[194:197], v160 offset:1024
	ds_read_b128 v[198:201], v159
	ds_read_b128 v[202:205], v159 offset:1024
	v_lshl_add_u64 v[206:207], v[206:207], 0, s[30:31]
	s_mov_b32 m0, s6
	v_lshl_add_u64 v[150:151], s[4:5], 0, v[132:133]
	v_readfirstlane_b32 s4, v173
	global_load_lds_dwordx4 v[206:207], off
	v_lshl_add_u64 v[150:151], v[150:151], 0, s[30:31]
	s_mov_b32 m0, s4
	s_nop 0
	global_load_lds_dwordx4 v[150:151], off
	s_barrier
	s_waitcnt lgkmcnt(0)
	s_cmp_lg_u32 s98, 0
	s_cbranch_scc1 .Lmy_glr_skip_8
	s_setprio 1
	s_waitcnt lgkmcnt(0)
	v_mfma_f32_16x16x32_bf16 v[124:127], v[174:177], v[128:131], v[124:127]
	v_mfma_f32_16x16x32_bf16 v[120:123], v[174:177], v[138:141], v[120:123]
	v_mfma_f32_16x16x32_bf16 v[116:119], v[182:185], v[128:131], v[116:119]
	v_mfma_f32_16x16x32_bf16 v[108:111], v[190:193], v[128:131], v[108:111]
	v_mfma_f32_16x16x32_bf16 v[104:107], v[190:193], v[138:141], v[104:107]
	v_mfma_f32_16x16x32_bf16 v[124:127], v[178:181], v[134:137], v[124:127]
	v_mfma_f32_16x16x32_bf16 v[120:123], v[178:181], v[142:145], v[120:123]
	v_mfma_f32_16x16x32_bf16 v[116:119], v[186:189], v[134:137], v[116:119]
	v_mfma_f32_16x16x32_bf16 v[112:115], v[182:185], v[138:141], v[112:115]
	v_mfma_f32_16x16x32_bf16 v[108:111], v[194:197], v[134:137], v[108:111]
	v_mfma_f32_16x16x32_bf16 v[104:107], v[194:197], v[142:145], v[104:107]
	v_mfma_f32_16x16x32_bf16 v[100:103], v[198:201], v[128:131], v[100:103]
	v_mfma_f32_16x16x32_bf16 v[96:99], v[198:201], v[138:141], v[96:99]
	v_mfma_f32_16x16x32_bf16 v[112:115], v[186:189], v[142:145], v[112:115]
	v_mfma_f32_16x16x32_bf16 v[206:209], v[202:205], v[134:137], v[100:103]
	v_mfma_f32_16x16x32_bf16 v[210:213], v[202:205], v[142:145], v[96:99]
	s_setprio 0
.Lmy_glr_skip_8:
	s_barrier
	s_nop 2
	ds_read_b128 v[96:99], v149
	ds_read_b128 v[100:103], v149 offset:1024
	ds_read_b128 v[214:217], v149 offset:2048
	ds_read_b128 v[218:221], v149 offset:3072
	s_barrier
	s_waitcnt lgkmcnt(0)
	s_cmp_lg_u32 s99, 0
	s_cbranch_scc1 .Lmy_glr_skip_9
	s_setprio 1
	s_waitcnt lgkmcnt(0)
	v_mfma_f32_16x16x32_bf16 v[88:91], v[174:177], v[214:217], v[88:91]
	v_mfma_f32_16x16x32_bf16 v[84:87], v[182:185], v[96:99], v[84:87]
	v_mfma_f32_16x16x32_bf16 v[68:71], v[198:201], v[96:99], v[68:71]
	v_mfma_f32_16x16x32_bf16 v[64:67], v[198:201], v[214:217], v[64:67]
	v_mfma_f32_16x16x32_bf16 v[92:95], v[174:177], v[96:99], v[92:95]
	v_mfma_f32_16x16x32_bf16 v[88:91], v[178:181], v[218:221], v[88:91]
	v_mfma_f32_16x16x32_bf16 v[84:87], v[186:189], v[100:103], v[84:87]
	v_mfma_f32_16x16x32_bf16 v[80:83], v[182:185], v[214:217], v[80:83]
	v_mfma_f32_16x16x32_bf16 v[76:79], v[190:193], v[96:99], v[76:79]
	v_mfma_f32_16x16x32_bf16 v[72:75], v[190:193], v[214:217], v[72:75]
	v_mfma_f32_16x16x32_bf16 v[68:71], v[202:205], v[100:103], v[68:71]
	v_mfma_f32_16x16x32_bf16 v[64:67], v[202:205], v[218:221], v[64:67]
	v_mfma_f32_16x16x32_bf16 v[92:95], v[178:181], v[100:103], v[92:95]
	v_mfma_f32_16x16x32_bf16 v[174:177], v[186:189], v[218:221], v[80:83]
	v_mfma_f32_16x16x32_bf16 v[178:181], v[194:197], v[100:103], v[76:79]
	v_mfma_f32_16x16x32_bf16 v[72:75], v[194:197], v[218:221], v[72:75]
	s_setprio 0
; #define LDA(dst, b, h) for (int m = 0; m < 4; ++m) for (int k = 0; k < 2; ++k) \
;     dst[m][k] = *reinterpret_cast<const bf16x8*>((char*)SA(b, h) + lds_byte(wr * 64 + m * 16 + fr, k * 32 + fq * 8))
; #define LDB(dst, b, h) for (int n = 0; n < 2; ++n) for (int k = 0; k < 2; ++k) \
;     dst[n][k] = *reinterpret_cast<const bf16x8*>((char*)SB(b, h) + lds_byte(wc * 32 + n * 16 + fr, k * 32 + fq * 8))
; #define MMA(ai, bj, At, Bq) do { __builtin_amdgcn_s_setprio(1); \
;     for (int m = 0; m < 4; ++m) for (int n = 0; n < 2; ++n) for (int k = 0; k < 2; ++k) \
;       acc[ai][bj][m][n] = __builtin_amdgcn_mfma_f32_16x16x32_bf16(At[m][k], Bq[n][k], acc[ai][bj][m][n], 0, 0, 0); \
;     __builtin_amdgcn_s_setprio(0); } while (0)
; #define WAIT_V(n) asm volatile("s_waitcnt vmcnt(" #n ")" ::: "memory")
; #define WAIT_L(n) asm volatile("s_waitcnt lgkmcnt(" #n ")" ::: "memory")
; #define BAR __builtin_amdgcn_s_barrier()
; template <class Epi>
; __device__ __forceinline__ void gemm_tile(const u16* __restrict__ A, const u16* __restrict__ Bt, int K,
;                                           int brow, int bcol, bool first, bool has_next, int nbrow, int nbcol, Epi epi) {
;     ...
;     LDA(At, 0, 1); WAIT_V(4); BAR; WAIT_L(0); MMA(1, 0, At, B0); MMA(1, 1, At, B1); BAR; }
;   { LDB(B0, 1, 0); LDA(At, 1, 0); WAIT_V(2); BAR; WAIT_L(0); MMA(0, 0, At, B0); BAR;
.Lmy_glr_skip_9:
	s_barrier
	ds_read_b128 v[76:79], v162 offset:16384
	ds_read_b128 v[80:83], v162 offset:17408
	ds_read_b128 v[182:185], v161 offset:16384
	ds_read_b128 v[186:189], v161 offset:17408
	ds_read_b128 v[190:193], v160 offset:16384
	ds_read_b128 v[194:197], v160 offset:17408
	ds_read_b128 v[198:201], v159 offset:16384
	ds_read_b128 v[202:205], v159 offset:17408
	s_waitcnt vmcnt(4)
	s_barrier
	s_waitcnt lgkmcnt(0)
	s_cmp_lg_u32 s98, 0
	s_cbranch_scc1 .Lmy_glr_skip_10
	s_setprio 1
	s_waitcnt lgkmcnt(0)
	v_mfma_f32_16x16x32_bf16 v[60:63], v[76:79], v[128:131], v[60:63]
	v_mfma_f32_16x16x32_bf16 v[48:51], v[182:185], v[138:141], v[48:51]
	v_mfma_f32_16x16x32_bf16 v[44:47], v[190:193], v[128:131], v[44:47]
	v_mfma_f32_16x16x32_bf16 v[60:63], v[80:83], v[134:137], v[60:63]
	v_mfma_f32_16x16x32_bf16 v[56:59], v[76:79], v[138:141], v[56:59]
	v_mfma_f32_16x16x32_bf16 v[52:55], v[182:185], v[128:131], v[52:55]
	v_mfma_f32_16x16x32_bf16 v[48:51], v[186:189], v[142:145], v[48:51]
	v_mfma_f32_16x16x32_bf16 v[44:47], v[194:197], v[134:137], v[44:47]
	v_mfma_f32_16x16x32_bf16 v[40:43], v[190:193], v[138:141], v[40:43]
	v_mfma_f32_16x16x32_bf16 v[36:39], v[198:201], v[128:131], v[36:39]
	v_mfma_f32_16x16x32_bf16 v[32:35], v[198:201], v[138:141], v[32:35]
	v_mfma_f32_16x16x32_bf16 v[230:233], v[80:83], v[142:145], v[56:59]
	v_mfma_f32_16x16x32_bf16 v[52:55], v[186:189], v[134:137], v[52:55]
	v_mfma_f32_16x16x32_bf16 v[234:237], v[194:197], v[142:145], v[40:43]
	v_mfma_f32_16x16x32_bf16 v[238:241], v[202:205], v[134:137], v[36:39]
	v_mfma_f32_16x16x32_bf16 v[32:35], v[202:205], v[142:145], v[32:35]
	s_setprio 0
.Lmy_glr_skip_10:
	s_cmp_lg_u32 s99, 0
	s_cbranch_scc1 .Lmy_glr_skip_11
	s_setprio 1
	v_mfma_f32_16x16x32_bf16 v[28:31], v[76:79], v[96:99], v[28:31]
	v_mfma_f32_16x16x32_bf16 v[24:27], v[76:79], v[214:217], v[24:27]
	v_mfma_f32_16x16x32_bf16 v[12:15], v[190:193], v[96:99], v[12:15]
	v_mfma_f32_16x16x32_bf16 v[8:11], v[190:193], v[214:217], v[8:11]
	v_mfma_f32_16x16x32_bf16 v[28:31], v[80:83], v[100:103], v[28:31]
	v_mfma_f32_16x16x32_bf16 v[24:27], v[80:83], v[218:221], v[24:27]
	v_mfma_f32_16x16x32_bf16 v[20:23], v[182:185], v[96:99], v[20:23]
	v_mfma_f32_16x16x32_bf16 v[16:19], v[182:185], v[214:217], v[16:19]
	v_mfma_f32_16x16x32_bf16 v[12:15], v[194:197], v[100:103], v[12:15]
	v_mfma_f32_16x16x32_bf16 v[8:11], v[194:197], v[218:221], v[8:11]
	v_mfma_f32_16x16x32_bf16 v[4:7], v[198:201], v[96:99], v[4:7]
	v_mfma_f32_16x16x32_bf16 v[0:3], v[198:201], v[214:217], v[0:3]
	v_mfma_f32_16x16x32_bf16 v[242:245], v[186:189], v[100:103], v[20:23]
	v_mfma_f32_16x16x32_bf16 v[182:185], v[186:189], v[218:221], v[16:19]
	v_mfma_f32_16x16x32_bf16 v[186:189], v[202:205], v[100:103], v[4:7]
	v_mfma_f32_16x16x32_bf16 v[190:193], v[202:205], v[218:221], v[0:3]
	s_setprio 0
.Lmy_glr_skip_11:
	s_barrier
	s_nop 1
	ds_read_b128 v[0:3], v148
	ds_read_b128 v[4:7], v148 offset:1024
	ds_read_b128 v[194:197], v148 offset:2048
	ds_read_b128 v[198:201], v148 offset:3072
	ds_read_b128 v[16:19], v162 offset:32768
	ds_read_b128 v[20:23], v162 offset:33792
	ds_read_b128 v[36:39], v161 offset:32768
	ds_read_b128 v[40:43], v161 offset:33792
	ds_read_b128 v[56:59], v160 offset:32768
	ds_read_b128 v[202:205], v160 offset:33792
	ds_read_b128 v[214:217], v159 offset:32768
	ds_read_b128 v[218:221], v159 offset:33792
	s_waitcnt vmcnt(2)
	s_barrier
	s_waitcnt lgkmcnt(0)
	s_cmp_lg_u32 s98, 0
	s_cbranch_scc1 .Lmy_glr_skip_12
	s_setprio 1
	s_waitcnt lgkmcnt(0)
	v_mfma_f32_16x16x32_bf16 v[76:79], v[16:19], v[0:3], v[124:127]
	v_mfma_f32_16x16x32_bf16 v[136:139], v[20:23], v[4:7], v[76:79]
	v_mfma_f32_16x16x32_bf16 v[76:79], v[16:19], v[194:197], v[120:123]
	v_mfma_f32_16x16x32_bf16 v[140:143], v[20:23], v[198:201], v[76:79]
	v_mfma_f32_16x16x32_bf16 v[76:79], v[36:39], v[0:3], v[116:119]
	v_mfma_f32_16x16x32_bf16 v[116:119], v[40:43], v[4:7], v[76:79]
	v_mfma_f32_16x16x32_bf16 v[76:79], v[36:39], v[194:197], v[112:115]
	v_mfma_f32_16x16x32_bf16 v[120:123], v[40:43], v[198:201], v[76:79]
	v_mfma_f32_16x16x32_bf16 v[76:79], v[56:59], v[0:3], v[108:111]
	v_mfma_f32_16x16x32_bf16 v[96:99], v[202:205], v[4:7], v[76:79]
	v_mfma_f32_16x16x32_bf16 v[76:79], v[56:59], v[194:197], v[104:107]
	v_mfma_f32_16x16x32_bf16 v[100:103], v[202:205], v[198:201], v[76:79]
	v_mfma_f32_16x16x32_bf16 v[76:79], v[214:217], v[0:3], v[206:209]
	v_mfma_f32_16x16x32_bf16 v[80:83], v[214:217], v[194:197], v[210:213]
	v_mfma_f32_16x16x32_bf16 v[76:79], v[218:221], v[4:7], v[76:79]
	v_mfma_f32_16x16x32_bf16 v[80:83], v[218:221], v[198:201], v[80:83]
	s_setprio 0
; #define LDA(dst, b, h) for (int m = 0; m < 4; ++m) for (int k = 0; k < 2; ++k) \
;     dst[m][k] = *reinterpret_cast<const bf16x8*>((char*)SA(b, h) + lds_byte(wr * 64 + m * 16 + fr, k * 32 + fq * 8))
; #define LDB(dst, b, h) for (int n = 0; n < 2; ++n) for (int k = 0; k < 2; ++k) \
;     dst[n][k] = *reinterpret_cast<const bf16x8*>((char*)SB(b, h) + lds_byte(wc * 32 + n * 16 + fr, k * 32 + fq * 8))
; #define MMA(ai, bj, At, Bq) do { __builtin_amdgcn_s_setprio(1); \
;     for (int m = 0; m < 4; ++m) for (int n = 0; n < 2; ++n) for (int k = 0; k < 2; ++k) \
;       acc[ai][bj][m][n] = __builtin_amdgcn_mfma_f32_16x16x32_bf16(At[m][k], Bq[n][k], acc[ai][bj][m][n], 0, 0, 0); \
;     __builtin_amdgcn_s_setprio(0); } while (0)
; #define WAIT_V(n) asm volatile("s_waitcnt vmcnt(" #n ")" ::: "memory")
; #define WAIT_L(n) asm volatile("s_waitcnt lgkmcnt(" #n ")" ::: "memory")
; #define BAR __builtin_amdgcn_s_barrier()
; template <class Epi>
; __device__ __forceinline__ void gemm_tile(const u16* __restrict__ A, const u16* __restrict__ Bt, int K,
;                                           int brow, int bcol, bool first, bool has_next, int nbrow, int nbcol, Epi epi) {
;     ...
;     LDB(B1, 1, 1); WAIT_V(0); BAR; WAIT_L(0); MMA(0, 1, At, B1); BAR;
;     LDA(At, 1, 1); BAR; WAIT_L(0); MMA(1, 0, At, B0); MMA(1, 1, At, B1); BAR; }
;   if (wr == 0) BAR;
.Lmy_glr_skip_12:
	s_barrier
	ds_read_b128 v[112:115], v147
	ds_read_b128 v[206:209], v147 offset:1024
	ds_read_b128 v[210:213], v147 offset:2048
	ds_read_b128 v[246:249], v147 offset:3072
	s_waitcnt vmcnt(0)
	s_barrier
	s_waitcnt lgkmcnt(0)
	s_cmp_lg_u32 s99, 0
	s_cbranch_scc1 .Lmy_glr_skip_13
	s_setprio 1
	s_waitcnt lgkmcnt(0)
	v_mfma_f32_16x16x32_bf16 v[92:95], v[16:19], v[112:115], v[92:95]
	v_mfma_f32_16x16x32_bf16 v[16:19], v[16:19], v[210:213], v[88:91]
	v_mfma_f32_16x16x32_bf16 v[148:151], v[20:23], v[246:249], v[16:19]
	v_mfma_f32_16x16x32_bf16 v[16:19], v[36:39], v[112:115], v[84:87]
	v_mfma_f32_16x16x32_bf16 v[124:127], v[40:43], v[206:209], v[16:19]
	v_mfma_f32_16x16x32_bf16 v[16:19], v[36:39], v[210:213], v[174:177]
	v_mfma_f32_16x16x32_bf16 v[128:131], v[40:43], v[246:249], v[16:19]
	v_mfma_f32_16x16x32_bf16 v[16:19], v[56:59], v[112:115], v[178:181]
	v_mfma_f32_16x16x32_bf16 v[104:107], v[202:205], v[206:209], v[16:19]
	v_mfma_f32_16x16x32_bf16 v[16:19], v[56:59], v[210:213], v[72:75]
	v_mfma_f32_16x16x32_bf16 v[108:111], v[202:205], v[246:249], v[16:19]
	v_mfma_f32_16x16x32_bf16 v[16:19], v[214:217], v[112:115], v[68:71]
	v_mfma_f32_16x16x32_bf16 v[84:87], v[218:221], v[206:209], v[16:19]
	v_mfma_f32_16x16x32_bf16 v[16:19], v[214:217], v[210:213], v[64:67]
	v_mfma_f32_16x16x32_bf16 v[144:147], v[20:23], v[206:209], v[92:95]
	v_mfma_f32_16x16x32_bf16 v[88:91], v[218:221], v[246:249], v[16:19]
	s_setprio 0
.Lmy_glr_skip_13:
	s_barrier
	ds_read_b128 v[68:71], v162 offset:49152
	ds_read_b128 v[72:75], v162 offset:50176
	ds_read_b128 v[92:95], v161 offset:49152
	ds_read_b128 v[174:177], v161 offset:50176
	ds_read_b128 v[178:181], v160 offset:49152
	ds_read_b128 v[202:205], v160 offset:50176
	ds_read_b128 v[214:217], v159 offset:49152
	ds_read_b128 v[218:221], v159 offset:50176
	s_barrier
	s_waitcnt lgkmcnt(0)
	s_cmp_lg_u32 s98, 0
	s_cbranch_scc1 .Lmy_glr_skip_14
	s_setprio 1
	s_waitcnt lgkmcnt(0)
	v_mfma_f32_16x16x32_bf16 v[16:19], v[68:71], v[0:3], v[60:63]
	v_mfma_f32_16x16x32_bf16 v[56:59], v[72:75], v[4:7], v[16:19]
	v_mfma_f32_16x16x32_bf16 v[16:19], v[68:71], v[194:197], v[230:233]
	v_mfma_f32_16x16x32_bf16 v[60:63], v[72:75], v[198:201], v[16:19]
	v_mfma_f32_16x16x32_bf16 v[16:19], v[92:95], v[0:3], v[52:55]
	v_mfma_f32_16x16x32_bf16 v[36:39], v[174:177], v[4:7], v[16:19]
	v_mfma_f32_16x16x32_bf16 v[16:19], v[92:95], v[194:197], v[48:51]
	v_mfma_f32_16x16x32_bf16 v[40:43], v[174:177], v[198:201], v[16:19]
	v_mfma_f32_16x16x32_bf16 v[16:19], v[178:181], v[0:3], v[44:47]
	v_mfma_f32_16x16x32_bf16 v[0:3], v[214:217], v[0:3], v[238:241]
	v_mfma_f32_16x16x32_bf16 v[16:19], v[202:205], v[4:7], v[16:19]
	v_mfma_f32_16x16x32_bf16 v[20:23], v[178:181], v[194:197], v[234:237]
	v_mfma_f32_16x16x32_bf16 v[0:3], v[218:221], v[4:7], v[0:3]
	v_mfma_f32_16x16x32_bf16 v[4:7], v[214:217], v[194:197], v[32:35]
	v_mfma_f32_16x16x32_bf16 v[20:23], v[202:205], v[198:201], v[20:23]
	v_mfma_f32_16x16x32_bf16 v[4:7], v[218:221], v[198:201], v[4:7]
	s_setprio 0
.Lmy_glr_skip_14:
	s_cmp_lg_u32 s99, 0
	s_cbranch_scc1 .Lmy_glr_skip_15
	s_setprio 1
	v_mfma_f32_16x16x32_bf16 v[24:27], v[68:71], v[210:213], v[24:27]
	v_mfma_f32_16x16x32_bf16 v[28:31], v[68:71], v[112:115], v[28:31]
	v_mfma_f32_16x16x32_bf16 v[68:71], v[72:75], v[246:249], v[24:27]
	v_mfma_f32_16x16x32_bf16 v[24:27], v[92:95], v[112:115], v[242:245]
	v_mfma_f32_16x16x32_bf16 v[44:47], v[174:177], v[206:209], v[24:27]
	v_mfma_f32_16x16x32_bf16 v[24:27], v[92:95], v[210:213], v[182:185]
	v_mfma_f32_16x16x32_bf16 v[12:15], v[178:181], v[112:115], v[12:15]
	v_mfma_f32_16x16x32_bf16 v[8:11], v[178:181], v[210:213], v[8:11]
	v_mfma_f32_16x16x32_bf16 v[64:67], v[72:75], v[206:209], v[28:31]
	v_mfma_f32_16x16x32_bf16 v[48:51], v[174:177], v[246:249], v[24:27]
	v_mfma_f32_16x16x32_bf16 v[24:27], v[202:205], v[206:209], v[12:15]
	v_mfma_f32_16x16x32_bf16 v[28:31], v[202:205], v[246:249], v[8:11]
	v_mfma_f32_16x16x32_bf16 v[8:11], v[214:217], v[112:115], v[186:189]
	v_mfma_f32_16x16x32_bf16 v[12:15], v[214:217], v[210:213], v[190:193]
	v_mfma_f32_16x16x32_bf16 v[8:11], v[218:221], v[206:209], v[8:11]
	v_mfma_f32_16x16x32_bf16 v[12:15], v[218:221], v[246:249], v[12:15]
	s_setprio 0
.Lmy_glr_skip_15:
	s_movk_i32 s4, 0x100
	v_cmp_gt_u32_e32 vcc, s4, v152
	s_barrier
	s_and_saveexec_b64 s[4:5], vcc
	s_cbranch_execz .LBB0_146
	s_barrier
